# batched loads: norm cA/cB preamble x4, forget-gate wT table, P0 silu table (no more load-wait per iteration)
# speedup vs baseline: 1.0035x; 1.0035x over previous
;     ...
;         for (int idx = tid; idx < BATCH * DM; idx += NTHR) { const int k = idx >> 2, b = idx & 3; const float cv = P.c[b * DM + k]; scl[idx] = cv / (1.0f + __expf(-cv)); }
.LBB0_9:
	v_ashrrev_i32_e32 v4, 2, v3
	v_and_b32_e32 v5, 0x1800, v2
	v_add_u32_e32 v4, v5, v4
	v_ashrrev_i32_e32 v5, 31, v4
	s_waitcnt lgkmcnt(0)
	v_lshl_add_u64 v[4:5], v[4:5], 2, s[4:5]
	v_add_co_u32_e32 v4, vcc, 0x1000, v4
	s_nop 1
	v_addc_co_u32_e32 v5, vcc, 0, v5, vcc
	global_load_dword v40, v[4:5], off offset:-4096
	global_load_dword v41, v[4:5], off offset:-3584
	global_load_dword v42, v[4:5], off offset:-3072
	global_load_dword v43, v[4:5], off offset:-2560
	global_load_dword v44, v[4:5], off offset:-2048
	global_load_dword v45, v[4:5], off offset:-1536
	global_load_dword v46, v[4:5], off offset:-1024
	global_load_dword v47, v[4:5], off offset:-512
	global_load_dword v48, v[4:5], off
	global_load_dword v49, v[4:5], off offset:512
	global_load_dword v50, v[4:5], off offset:1024
	global_load_dword v51, v[4:5], off offset:1536
	global_load_dword v52, v[4:5], off offset:2048
	global_load_dword v53, v[4:5], off offset:2560
	global_load_dword v54, v[4:5], off offset:3072
	global_load_dword v55, v[4:5], off offset:3584
	s_waitcnt vmcnt(0)
	v_mul_f32_e32 v5, 0xbfb8aa3b, v40
	v_exp_f32_e32 v5, v5
	s_nop 0
	v_add_f32_e32 v5, 1.0, v5
	v_div_scale_f32 v6, s[48:49], v5, v5, v40
	v_rcp_f32_e32 v7, v6
	v_div_scale_f32 v8, vcc, v40, v5, v40
	v_fma_f32 v9, -v6, v7, 1.0
	v_fmac_f32_e32 v7, v9, v7
	v_mul_f32_e32 v9, v8, v7
	v_fma_f32 v10, -v6, v9, v8
	v_fmac_f32_e32 v9, v10, v7
	v_fma_f32 v6, -v6, v9, v8
	v_div_fmas_f32 v6, v6, v7, v9
	v_div_fixup_f32 v4, v6, v5, v40
	ds_write_b32 v1, v4
	v_mul_f32_e32 v5, 0xbfb8aa3b, v41
	v_exp_f32_e32 v5, v5
	s_nop 0
	v_add_f32_e32 v5, 1.0, v5
	v_div_scale_f32 v6, s[48:49], v5, v5, v41
	v_rcp_f32_e32 v7, v6
	v_div_scale_f32 v8, vcc, v41, v5, v41
	v_fma_f32 v9, -v6, v7, 1.0
	v_fmac_f32_e32 v7, v9, v7
	v_mul_f32_e32 v9, v8, v7
	v_fma_f32 v10, -v6, v9, v8
	v_fmac_f32_e32 v9, v10, v7
	v_fma_f32 v6, -v6, v9, v8
	v_div_fmas_f32 v6, v6, v7, v9
	v_div_fixup_f32 v4, v6, v5, v41
	ds_write_b32 v1, v4 offset:2048
	v_mul_f32_e32 v5, 0xbfb8aa3b, v42
	v_exp_f32_e32 v5, v5
	s_nop 0
	v_add_f32_e32 v5, 1.0, v5
	v_div_scale_f32 v6, s[48:49], v5, v5, v42
	v_rcp_f32_e32 v7, v6
	v_div_scale_f32 v8, vcc, v42, v5, v42
	v_fma_f32 v9, -v6, v7, 1.0
	v_fmac_f32_e32 v7, v9, v7
	v_mul_f32_e32 v9, v8, v7
	v_fma_f32 v10, -v6, v9, v8
	v_fmac_f32_e32 v9, v10, v7
	v_fma_f32 v6, -v6, v9, v8
	v_div_fmas_f32 v6, v6, v7, v9
	v_div_fixup_f32 v4, v6, v5, v42
	ds_write_b32 v1, v4 offset:4096
	v_mul_f32_e32 v5, 0xbfb8aa3b, v43
	v_exp_f32_e32 v5, v5
	s_nop 0
	v_add_f32_e32 v5, 1.0, v5
	v_div_scale_f32 v6, s[48:49], v5, v5, v43
	v_rcp_f32_e32 v7, v6
	v_div_scale_f32 v8, vcc, v43, v5, v43
	v_fma_f32 v9, -v6, v7, 1.0
	v_fmac_f32_e32 v7, v9, v7
	v_mul_f32_e32 v9, v8, v7
	v_fma_f32 v10, -v6, v9, v8
	v_fmac_f32_e32 v9, v10, v7
	v_fma_f32 v6, -v6, v9, v8
	v_div_fmas_f32 v6, v6, v7, v9
	v_div_fixup_f32 v4, v6, v5, v43
	ds_write_b32 v1, v4 offset:6144
	v_mul_f32_e32 v5, 0xbfb8aa3b, v44
	v_exp_f32_e32 v5, v5
	s_nop 0
	v_add_f32_e32 v5, 1.0, v5
	v_div_scale_f32 v6, s[48:49], v5, v5, v44
	v_rcp_f32_e32 v7, v6
	v_div_scale_f32 v8, vcc, v44, v5, v44
	v_fma_f32 v9, -v6, v7, 1.0
	v_fmac_f32_e32 v7, v9, v7
	v_mul_f32_e32 v9, v8, v7
	v_fma_f32 v10, -v6, v9, v8
	v_fmac_f32_e32 v9, v10, v7
	v_fma_f32 v6, -v6, v9, v8
	v_div_fmas_f32 v6, v6, v7, v9
	v_div_fixup_f32 v4, v6, v5, v44
	ds_write_b32 v1, v4 offset:8192
	v_mul_f32_e32 v5, 0xbfb8aa3b, v45
	v_exp_f32_e32 v5, v5
	s_nop 0
	v_add_f32_e32 v5, 1.0, v5
	v_div_scale_f32 v6, s[48:49], v5, v5, v45
	v_rcp_f32_e32 v7, v6
	v_div_scale_f32 v8, vcc, v45, v5, v45
	v_fma_f32 v9, -v6, v7, 1.0
	v_fmac_f32_e32 v7, v9, v7
	v_mul_f32_e32 v9, v8, v7
	v_fma_f32 v10, -v6, v9, v8
	v_fmac_f32_e32 v9, v10, v7
	v_fma_f32 v6, -v6, v9, v8
	v_div_fmas_f32 v6, v6, v7, v9
	v_div_fixup_f32 v4, v6, v5, v45
	ds_write_b32 v1, v4 offset:10240
	v_mul_f32_e32 v5, 0xbfb8aa3b, v46
	v_exp_f32_e32 v5, v5
	s_nop 0
	v_add_f32_e32 v5, 1.0, v5
	v_div_scale_f32 v6, s[48:49], v5, v5, v46
	v_rcp_f32_e32 v7, v6
	v_div_scale_f32 v8, vcc, v46, v5, v46
	v_fma_f32 v9, -v6, v7, 1.0
	v_fmac_f32_e32 v7, v9, v7
	v_mul_f32_e32 v9, v8, v7
	v_fma_f32 v10, -v6, v9, v8
	v_fmac_f32_e32 v9, v10, v7
	v_fma_f32 v6, -v6, v9, v8
	v_div_fmas_f32 v6, v6, v7, v9
;     ...
;         for (int idx = tid; idx < BATCH * DM; idx += NTHR) { const int k = idx >> 2, b = idx & 3; const float cv = P.c[b * DM + k]; scl[idx] = cv / (1.0f + __expf(-cv)); }
	v_div_fixup_f32 v4, v6, v5, v46
	ds_write_b32 v1, v4 offset:12288
	v_mul_f32_e32 v5, 0xbfb8aa3b, v47
	v_exp_f32_e32 v5, v5
	s_nop 0
	v_add_f32_e32 v5, 1.0, v5
	v_div_scale_f32 v6, s[48:49], v5, v5, v47
	v_rcp_f32_e32 v7, v6
	v_div_scale_f32 v8, vcc, v47, v5, v47
	v_fma_f32 v9, -v6, v7, 1.0
	v_fmac_f32_e32 v7, v9, v7
	v_mul_f32_e32 v9, v8, v7
	v_fma_f32 v10, -v6, v9, v8
	v_fmac_f32_e32 v9, v10, v7
	v_fma_f32 v6, -v6, v9, v8
	v_div_fmas_f32 v6, v6, v7, v9
	v_div_fixup_f32 v4, v6, v5, v47
	ds_write_b32 v1, v4 offset:14336
	v_mul_f32_e32 v5, 0xbfb8aa3b, v48
	v_exp_f32_e32 v5, v5
	s_nop 0
	v_add_f32_e32 v5, 1.0, v5
	v_div_scale_f32 v6, s[48:49], v5, v5, v48
	v_rcp_f32_e32 v7, v6
	v_div_scale_f32 v8, vcc, v48, v5, v48
	v_fma_f32 v9, -v6, v7, 1.0
	v_fmac_f32_e32 v7, v9, v7
	v_mul_f32_e32 v9, v8, v7
	v_fma_f32 v10, -v6, v9, v8
	v_fmac_f32_e32 v9, v10, v7
	v_fma_f32 v6, -v6, v9, v8
	v_div_fmas_f32 v6, v6, v7, v9
	v_div_fixup_f32 v4, v6, v5, v48
	ds_write_b32 v1, v4 offset:16384
	v_mul_f32_e32 v5, 0xbfb8aa3b, v49
	v_exp_f32_e32 v5, v5
	s_nop 0
	v_add_f32_e32 v5, 1.0, v5
	v_div_scale_f32 v6, s[48:49], v5, v5, v49
	v_rcp_f32_e32 v7, v6
	v_div_scale_f32 v8, vcc, v49, v5, v49
	v_fma_f32 v9, -v6, v7, 1.0
	v_fmac_f32_e32 v7, v9, v7
	v_mul_f32_e32 v9, v8, v7
	v_fma_f32 v10, -v6, v9, v8
	v_fmac_f32_e32 v9, v10, v7
	v_fma_f32 v6, -v6, v9, v8
	v_div_fmas_f32 v6, v6, v7, v9
	v_div_fixup_f32 v4, v6, v5, v49
	ds_write_b32 v1, v4 offset:18432
	v_mul_f32_e32 v5, 0xbfb8aa3b, v50
	v_exp_f32_e32 v5, v5
	s_nop 0
	v_add_f32_e32 v5, 1.0, v5
	v_div_scale_f32 v6, s[48:49], v5, v5, v50
	v_rcp_f32_e32 v7, v6
	v_div_scale_f32 v8, vcc, v50, v5, v50
	v_fma_f32 v9, -v6, v7, 1.0
	v_fmac_f32_e32 v7, v9, v7
	v_mul_f32_e32 v9, v8, v7
	v_fma_f32 v10, -v6, v9, v8
	v_fmac_f32_e32 v9, v10, v7
	v_fma_f32 v6, -v6, v9, v8
	v_div_fmas_f32 v6, v6, v7, v9
	v_div_fixup_f32 v4, v6, v5, v50
	ds_write_b32 v1, v4 offset:20480
	v_mul_f32_e32 v5, 0xbfb8aa3b, v51
	v_exp_f32_e32 v5, v5
	s_nop 0
	v_add_f32_e32 v5, 1.0, v5
	v_div_scale_f32 v6, s[48:49], v5, v5, v51
	v_rcp_f32_e32 v7, v6
	v_div_scale_f32 v8, vcc, v51, v5, v51
	v_fma_f32 v9, -v6, v7, 1.0
	v_fmac_f32_e32 v7, v9, v7
	v_mul_f32_e32 v9, v8, v7
	v_fma_f32 v10, -v6, v9, v8
	v_fmac_f32_e32 v9, v10, v7
	v_fma_f32 v6, -v6, v9, v8
	v_div_fmas_f32 v6, v6, v7, v9
	v_div_fixup_f32 v4, v6, v5, v51
	ds_write_b32 v1, v4 offset:22528
	v_mul_f32_e32 v5, 0xbfb8aa3b, v52
	v_exp_f32_e32 v5, v5
	s_nop 0
	v_add_f32_e32 v5, 1.0, v5
	v_div_scale_f32 v6, s[48:49], v5, v5, v52
	v_rcp_f32_e32 v7, v6
	v_div_scale_f32 v8, vcc, v52, v5, v52
	v_fma_f32 v9, -v6, v7, 1.0
	v_fmac_f32_e32 v7, v9, v7
	v_mul_f32_e32 v9, v8, v7
	v_fma_f32 v10, -v6, v9, v8
	v_fmac_f32_e32 v9, v10, v7
	v_fma_f32 v6, -v6, v9, v8
	v_div_fmas_f32 v6, v6, v7, v9
	v_div_fixup_f32 v4, v6, v5, v52
	ds_write_b32 v1, v4 offset:24576
	v_mul_f32_e32 v5, 0xbfb8aa3b, v53
	v_exp_f32_e32 v5, v5
	s_nop 0
	v_add_f32_e32 v5, 1.0, v5
	v_div_scale_f32 v6, s[48:49], v5, v5, v53
	v_rcp_f32_e32 v7, v6
	v_div_scale_f32 v8, vcc, v53, v5, v53
	v_fma_f32 v9, -v6, v7, 1.0
	v_fmac_f32_e32 v7, v9, v7
	v_mul_f32_e32 v9, v8, v7
	v_fma_f32 v10, -v6, v9, v8
	v_fmac_f32_e32 v9, v10, v7
	v_fma_f32 v6, -v6, v9, v8
	v_div_fmas_f32 v6, v6, v7, v9
	v_div_fixup_f32 v4, v6, v5, v53
	ds_write_b32 v1, v4 offset:26624
	v_mul_f32_e32 v5, 0xbfb8aa3b, v54
	v_exp_f32_e32 v5, v5
	s_nop 0
	v_add_f32_e32 v5, 1.0, v5
	v_div_scale_f32 v6, s[48:49], v5, v5, v54
	v_rcp_f32_e32 v7, v6
	v_div_scale_f32 v8, vcc, v54, v5, v54
	v_fma_f32 v9, -v6, v7, 1.0
	v_fmac_f32_e32 v7, v9, v7
	v_mul_f32_e32 v9, v8, v7
	v_fma_f32 v10, -v6, v9, v8
	v_fmac_f32_e32 v9, v10, v7
	v_fma_f32 v6, -v6, v9, v8
	v_div_fmas_f32 v6, v6, v7, v9
	v_div_fixup_f32 v4, v6, v5, v54
	ds_write_b32 v1, v4 offset:28672
	v_mul_f32_e32 v5, 0xbfb8aa3b, v55
	v_exp_f32_e32 v5, v5
	s_nop 0
	v_add_f32_e32 v5, 1.0, v5
	v_div_scale_f32 v6, s[48:49], v5, v5, v55
	v_rcp_f32_e32 v7, v6
	v_div_scale_f32 v8, vcc, v55, v5, v55
	v_fma_f32 v9, -v6, v7, 1.0
	v_fmac_f32_e32 v7, v9, v7
	v_mul_f32_e32 v9, v8, v7
	v_fma_f32 v10, -v6, v9, v8
	v_fmac_f32_e32 v9, v10, v7
	v_fma_f32 v6, -v6, v9, v8
	v_div_fmas_f32 v6, v6, v7, v9
	v_div_fixup_f32 v4, v6, v5, v55
	ds_write_b32 v1, v4 offset:30720

; template <int MODE, bool INBF> ...
;     ...
;         for (int cidx = tid; cidx < DM; cidx += NTHR) { const float g = gvec[cidx];
;             if (MODE != 1) { cA[cidx] = g * (1.0f + scale[(size_t)b * MODS + cidx]); cB[cidx] = shift[(size_t)b * MODS + cidx]; } else { cA[cidx] = g; cB[cidx] = 0.f; } }
.LBB0_119:
	v_add_co_u32_e32 v6, vcc, 0x1000, v0
	s_nop 1
	v_addc_co_u32_e32 v7, vcc, 0, v1, vcc
	v_add_co_u32_e32 v8, vcc, 0x3000, v0
	s_nop 1
	v_addc_co_u32_e32 v9, vcc, 0, v1, vcc
	v_add_co_u32_e32 v2, vcc, 0x1000, v2
	s_nop 1
	v_addc_co_u32_e32 v3, vcc, 0, v3, vcc
	global_load_dword v234, v[8:9], off offset:-4096
	global_load_dword v235, v[8:9], off offset:-2048
	global_load_dword v236, v[8:9], off
	global_load_dword v237, v[8:9], off offset:2048
	global_load_dword v238, v[2:3], off offset:-4096
	global_load_dword v239, v[2:3], off offset:-2048
	global_load_dword v240, v[2:3], off
	global_load_dword v241, v[2:3], off offset:2048
	global_load_dword v242, v[6:7], off offset:-4096
	global_load_dword v243, v[6:7], off offset:-2048
	global_load_dword v244, v[6:7], off
	global_load_dword v245, v[6:7], off offset:2048
	s_waitcnt vmcnt(4)
	v_add_f32_e32 v234, 1.0, v234
	v_add_f32_e32 v235, 1.0, v235
	v_add_f32_e32 v236, 1.0, v236
	v_add_f32_e32 v237, 1.0, v237
	v_mul_f32_e32 v234, v238, v234
	v_mul_f32_e32 v235, v239, v235
	v_mul_f32_e32 v236, v240, v236
	v_mul_f32_e32 v237, v241, v237
	ds_write_b32 v4, v234
	ds_write_b32 v4, v235 offset:2048
	ds_write_b32 v4, v236 offset:4096
	ds_write_b32 v4, v237 offset:6144
	s_waitcnt vmcnt(0)
	ds_write_b32 v4, v242 offset:8192
	ds_write_b32 v4, v243 offset:10240
	ds_write_b32 v4, v244 offset:12288
	ds_write_b32 v4, v245 offset:14336

; template <int MODE, bool INBF> ...
;     ...
;         if (MODE == 2 && blk == (int)blockIdx.x) {
;             for (int idx = tid; idx < DM * 16; idx += NTHR) { const int k = idx >> 4, hh = idx & 15; wT[hh * WTP + k] = wf[(size_t)k * NBIN + 3 * DM + hh]; } }
.LBB0_626:
	s_or_b64 exec, exec, s[18:19]
	s_cmp_eq_u32 s60, s2
	s_cselect_b64 s[18:19], -1, 0
	s_and_b64 s[26:27], s[24:25], s[18:19]
	s_and_saveexec_b64 s[18:19], s[26:27]
	s_cbranch_execz .LBB0_638
	v_lshrrev_b32_e32 v0, 4, v16
	v_mov_b64_e32 v[4:5], s[20:21]
	v_lshlrev_b32_e32 v18, 2, v28
	v_mad_i64_i32 v[2:3], s[28:29], v0, s48, v[4:5]
	v_lshl_add_u64 v[2:3], v[2:3], 0, v[18:19]
	v_add_co_u32_e32 v2, vcc, 0x6000, v2
	s_nop 1
	v_addc_co_u32_e32 v3, vcc, 0, v3, vcc
	v_lshl_add_u32 v1, v0, 2, v104
	s_mov_b32 s26, 0xc0800
	s_mov_b32 s27, 0
	s_mov_b32 s28, 0
.Lwt_fill_loop:
	global_load_dword v34, v[2:3], off
	v_lshl_add_u64 v[2:3], v[2:3], 0, s[26:27]
	global_load_dword v35, v[2:3], off
	v_lshl_add_u64 v[2:3], v[2:3], 0, s[26:27]
	global_load_dword v36, v[2:3], off
	v_lshl_add_u64 v[2:3], v[2:3], 0, s[26:27]
	global_load_dword v37, v[2:3], off
	v_lshl_add_u64 v[2:3], v[2:3], 0, s[26:27]
	global_load_dword v38, v[2:3], off
	v_lshl_add_u64 v[2:3], v[2:3], 0, s[26:27]
	global_load_dword v39, v[2:3], off
	v_lshl_add_u64 v[2:3], v[2:3], 0, s[26:27]
	global_load_dword v40, v[2:3], off
	v_lshl_add_u64 v[2:3], v[2:3], 0, s[26:27]
	global_load_dword v41, v[2:3], off
	v_lshl_add_u64 v[2:3], v[2:3], 0, s[26:27]
	global_load_dword v42, v[2:3], off
	v_lshl_add_u64 v[2:3], v[2:3], 0, s[26:27]
	global_load_dword v43, v[2:3], off
	v_lshl_add_u64 v[2:3], v[2:3], 0, s[26:27]
	global_load_dword v44, v[2:3], off
	v_lshl_add_u64 v[2:3], v[2:3], 0, s[26:27]
	global_load_dword v45, v[2:3], off
	v_lshl_add_u64 v[2:3], v[2:3], 0, s[26:27]
	global_load_dword v46, v[2:3], off
	v_lshl_add_u64 v[2:3], v[2:3], 0, s[26:27]
	global_load_dword v47, v[2:3], off
	v_lshl_add_u64 v[2:3], v[2:3], 0, s[26:27]
	global_load_dword v48, v[2:3], off
	v_lshl_add_u64 v[2:3], v[2:3], 0, s[26:27]
	global_load_dword v49, v[2:3], off
	v_lshl_add_u64 v[2:3], v[2:3], 0, s[26:27]
	global_load_dword v50, v[2:3], off
	v_lshl_add_u64 v[2:3], v[2:3], 0, s[26:27]
	global_load_dword v51, v[2:3], off
	v_lshl_add_u64 v[2:3], v[2:3], 0, s[26:27]
	global_load_dword v52, v[2:3], off
	v_lshl_add_u64 v[2:3], v[2:3], 0, s[26:27]
	global_load_dword v53, v[2:3], off
	v_lshl_add_u64 v[2:3], v[2:3], 0, s[26:27]
	global_load_dword v54, v[2:3], off
	v_lshl_add_u64 v[2:3], v[2:3], 0, s[26:27]
	global_load_dword v55, v[2:3], off
	v_lshl_add_u64 v[2:3], v[2:3], 0, s[26:27]
	global_load_dword v56, v[2:3], off
	v_lshl_add_u64 v[2:3], v[2:3], 0, s[26:27]
	global_load_dword v57, v[2:3], off
	v_lshl_add_u64 v[2:3], v[2:3], 0, s[26:27]
	global_load_dword v58, v[2:3], off
	v_lshl_add_u64 v[2:3], v[2:3], 0, s[26:27]
	global_load_dword v59, v[2:3], off
	v_lshl_add_u64 v[2:3], v[2:3], 0, s[26:27]
	global_load_dword v60, v[2:3], off
	v_lshl_add_u64 v[2:3], v[2:3], 0, s[26:27]
	global_load_dword v61, v[2:3], off
	v_lshl_add_u64 v[2:3], v[2:3], 0, s[26:27]
	global_load_dword v62, v[2:3], off
	v_lshl_add_u64 v[2:3], v[2:3], 0, s[26:27]
	global_load_dword v63, v[2:3], off
	v_lshl_add_u64 v[2:3], v[2:3], 0, s[26:27]
	global_load_dword v64, v[2:3], off
	v_lshl_add_u64 v[2:3], v[2:3], 0, s[26:27]
	global_load_dword v65, v[2:3], off
	v_lshl_add_u64 v[2:3], v[2:3], 0, s[26:27]
	s_waitcnt vmcnt(0)
	ds_write_b32 v1, v34 offset:16384
	ds_write_b32 v1, v35 offset:16512
	ds_write_b32 v1, v36 offset:16640
	ds_write_b32 v1, v37 offset:16768
	ds_write_b32 v1, v38 offset:16896
	ds_write_b32 v1, v39 offset:17024
	ds_write_b32 v1, v40 offset:17152
	ds_write_b32 v1, v41 offset:17280
	ds_write_b32 v1, v42 offset:17408
	ds_write_b32 v1, v43 offset:17536
	ds_write_b32 v1, v44 offset:17664
	ds_write_b32 v1, v45 offset:17792
	ds_write_b32 v1, v46 offset:17920
	ds_write_b32 v1, v47 offset:18048
	ds_write_b32 v1, v48 offset:18176
	ds_write_b32 v1, v49 offset:18304
	ds_write_b32 v1, v50 offset:18432
	ds_write_b32 v1, v51 offset:18560
	ds_write_b32 v1, v52 offset:18688
	ds_write_b32 v1, v53 offset:18816
	ds_write_b32 v1, v54 offset:18944
	ds_write_b32 v1, v55 offset:19072
	ds_write_b32 v1, v56 offset:19200
	ds_write_b32 v1, v57 offset:19328
	ds_write_b32 v1, v58 offset:19456
	ds_write_b32 v1, v59 offset:19584
	ds_write_b32 v1, v60 offset:19712
	ds_write_b32 v1, v61 offset:19840
	ds_write_b32 v1, v62 offset:19968
	ds_write_b32 v1, v63 offset:20096
	ds_write_b32 v1, v64 offset:20224
	ds_write_b32 v1, v65 offset:20352
	v_add_u32_e32 v1, 0x1000, v1
	s_add_i32 s28, s28, 1
	s_cmp_lt_u32 s28, 2
	s_cbranch_scc1 .Lwt_fill_loop
